# prep phase: g/beta loads first with counted vmcnt so the cumsum chain overlaps the fragment loads; K fragments of tile rows 2,3 requested together
# baseline (speedup 1.0000x reference)
; __device__ __forceinline__ void phase_prep(const Args& a, PG8_LAS unsigned char* lds) {
;     ...
;         bf16x8 ak[4], aq[4], bkf[2][4];
; #pragma unroll
;         for (int s = 0; s < 4; ++s) { ak[s] = *(const bf16x8*)(kbase + (size_t)(16 * lw + r) * 512 + 32 * s + 8 * q); aq[s] = *(const bf16x8*)(qbase + (size_t)(16 * lw + r) * 512 + 32 * s + 8 * q); }
; #pragma unroll
;         for (int tj = 0; tj < 2; ++tj)
; #pragma unroll
;             for (int s = 0; s < 4; ++s) bkf[tj][s] = *(const bf16x8*)(kbase + (size_t)(16 * tj + r) * 512 + 32 * s + 8 * q);
;         bf16x8 pv[2][2], pk[2][2];
;         if (role != 0) {
; #pragma unroll
;         for (int cc = 0; cc < 2; ++cc) { const int ct = 2 * lw + cc;
;             pv[cc][0] = *(const bf16x8*)(vTb + (size_t)(16 * ct + r) * 64 + 8 * q); pv[cc][1] = *(const bf16x8*)(vTb + (size_t)(16 * ct + r) * 64 + 32 + 8 * q);
;             pk[cc][0] = *(const bf16x8*)(kTb + (size_t)(16 * ct + r) * 64 + 8 * q); pk[cc][1] = *(const bf16x8*)(kTb + (size_t)(16 * ct + r) * 64 + 32 + 8 * q); } }
;         float gv = gB[(r0 + lane) * 4 + h];
; #pragma unroll
;         for (int off = 1; off < 64; off <<= 1) { const float t = __shfl_up(gv, off); if (lane >= off) gv += t; }
;         const float g63 = __shfl(gv, 63);
;         if (lw == 0) { sG[lane] = gv; sB[lane] = betaB[(r0 + lane) * 4 + h]; sE[lane] = __expf(gv); sK[lane] = __expf(g63 - gv); }
;         if ((tid & 255) == 0) glast[item] = __expf(g63);
.LBB0_253:
	s_ashr_i32 s18, s38, 1
	s_lshl_b32 s14, s38, 1
	s_and_b32 s14, s14, 2
	s_ashr_i32 s19, s18, 31
	s_add_i32 s26, s14, s33
	s_lshl_b64 s[20:21], s[18:19], 15
	s_lshl_b64 s[24:25], s[18:19], 16
	v_readlane_b32 s14, v253, 43
	s_add_u32 s22, s14, s24
	v_readlane_b32 s14, v253, 44
	s_addc_u32 s23, s14, s25
	s_lshl_b32 s14, s26, 7
	s_lshl_b32 s27, s26, 8
	s_add_u32 s22, s22, s27
	s_addc_u32 s23, s23, 0
	v_readlane_b32 s39, v253, 45
	s_add_u32 s39, s39, s24
	v_readlane_b32 s40, v253, 46
	s_addc_u32 s40, s40, s25
	s_add_u32 vcc_lo, s39, s27
	s_addc_u32 vcc_hi, s40, 0
	v_mov_b32_e32 v107, v97
	v_lshl_add_u64 v[32:33], vcc, 0, v[106:107]
	v_lshl_add_u64 v[34:35], s[22:23], 0, v[106:107]
	v_lshl_add_u64 v[32:33], v[32:33], 0, v[96:97]
	v_lshl_add_u64 v[36:37], v[34:35], 0, v[96:97]
	s_lshl_b64 s[98:99], s[18:19], 8
	s_mov_b32 s100, s26
	s_mov_b32 s101, s15
	v_mov_b32_e32 v129, s99
	v_or_b32_e32 v128, s98, v98
	v_lshl_add_u64 v[128:129], v[128:129], 0, s[100:101]
	v_lshl_add_u64 v[230:231], v[128:129], 2, s[8:9]
	global_load_dword v234, v[230:231], off
	v_readlane_b32 s100, v253, 49
	v_readlane_b32 s101, v253, 50
	s_nop 1
	v_lshl_add_u64 v[232:233], v[128:129], 2, s[100:101]
	global_load_dword v111, v[232:233], off
	global_load_dwordx4 v[56:59], v[32:33], off
	global_load_dwordx4 v[48:51], v[32:33], off offset:64
	global_load_dwordx4 v[60:63], v[36:37], off
	global_load_dwordx4 v[52:55], v[36:37], off offset:64
	global_load_dwordx4 v[40:43], v[32:33], off offset:128
	s_nop 0
	global_load_dwordx4 v[32:35], v[32:33], off offset:192
	s_nop 0
	global_load_dwordx4 v[44:47], v[36:37], off offset:128
	s_nop 0
	global_load_dwordx4 v[36:39], v[36:37], off offset:192
	v_lshl_add_u64 v[64:65], vcc, 0, v[96:97]
	v_mov_b32_e32 v109, v97
	v_lshl_add_u64 v[126:127], v[64:65], 0, v[108:109]
	s_movk_i32 s22, 0x4000
	v_add_co_u32_e32 v64, vcc, s22, v126
	global_load_dwordx4 v[92:95], v[126:127], off
	global_load_dwordx4 v[88:91], v[126:127], off offset:64
	global_load_dwordx4 v[84:87], v[126:127], off offset:128
	global_load_dwordx4 v[80:83], v[126:127], off offset:192
	v_addc_co_u32_e32 v65, vcc, 0, v127, vcc
	global_load_dwordx4 v[76:79], v[64:65], off
	global_load_dwordx4 v[72:75], v[64:65], off offset:64
	global_load_dwordx4 v[68:71], v[64:65], off offset:128
	s_nop 0
	global_load_dwordx4 v[64:67], v[64:65], off offset:192
	s_lshl_b64 s[22:23], s[14:15], 6
	s_add_u32 s20, s22, s20
	s_addc_u32 s21, s23, s21
	s_lshl_b64 s[22:23], s[20:21], 1
	s_add_u32 s20, s10, s22
	s_addc_u32 s21, s11, s23
	v_readlane_b32 s14, v253, 47
	v_readlane_b32 s40, v253, 53
	s_add_u32 s22, s14, s22
	v_readlane_b32 s14, v253, 48
	v_readlane_b32 s41, v253, 54
	s_addc_u32 s23, s14, s23
	s_waitcnt vmcnt(16)
	s_andn2_b64 vcc, exec, s[40:41]
	s_cbranch_vccnz .LBB0_255
	v_mov_b32_e32 v115, v97
	v_lshl_add_u64 v[0:1], s[22:23], 0, v[114:115]
	v_lshl_add_u64 v[8:9], s[20:21], 0, v[114:115]
	v_lshl_add_u64 v[16:17], v[0:1], 0, v[96:97]
	v_lshl_add_u64 v[24:25], v[8:9], 0, v[96:97]
	global_load_dwordx4 v[0:3], v[16:17], off
	global_load_dwordx4 v[4:7], v[16:17], off offset:64
	global_load_dwordx4 v[8:11], v[24:25], off
	global_load_dwordx4 v[12:15], v[24:25], off offset:64
	global_load_dwordx4 v[20:23], v[16:17], off offset:2048
	global_load_dwordx4 v[28:31], v[16:17], off offset:2112
	s_nop 0
	global_load_dwordx4 v[16:19], v[24:25], off offset:2048
	s_nop 0
	global_load_dwordx4 v[24:27], v[24:25], off offset:2112
.LBB0_255:
	v_mov_b32_e32 v107, v234
	v_readlane_b32 s40, v253, 59
	v_readlane_b32 s41, v253, 60
	ds_bpermute_b32 v109, v131, v107
	s_waitcnt lgkmcnt(0)
	v_add_f32_e32 v109, v107, v109
	v_cndmask_b32_e64 v107, v109, v107, s[62:63]
	ds_bpermute_b32 v109, v132, v107
	s_waitcnt lgkmcnt(0)
	v_add_f32_e32 v109, v107, v109
	v_cndmask_b32_e64 v107, v109, v107, s[40:41]
	ds_bpermute_b32 v109, v133, v107
	v_readlane_b32 s40, v253, 61
	v_readlane_b32 s41, v253, 62
	s_waitcnt lgkmcnt(0)
	v_add_f32_e32 v109, v107, v109
	v_cndmask_b32_e64 v107, v109, v107, s[40:41]
	ds_bpermute_b32 v109, v134, v107
	v_readlane_b32 s40, v253, 63
	v_readlane_b32 s41, v252, 0
	s_waitcnt lgkmcnt(0)
	v_add_f32_e32 v109, v107, v109
	v_cndmask_b32_e64 v107, v109, v107, s[40:41]
	ds_bpermute_b32 v109, v135, v107
	v_readlane_b32 s40, v252, 1
	v_readlane_b32 s41, v252, 2
	s_waitcnt lgkmcnt(0)
	v_add_f32_e32 v109, v107, v109
	v_cndmask_b32_e64 v107, v109, v107, s[40:41]
	ds_bpermute_b32 v109, v136, v107
	v_readlane_b32 s40, v252, 3
	v_readlane_b32 s41, v252, 4
	s_waitcnt lgkmcnt(0)
	v_add_f32_e32 v109, v107, v109
	v_cndmask_b32_e64 v109, v109, v107, s[40:41]
	ds_bpermute_b32 v107, v99, v109
	v_readlane_b32 s40, v253, 55
	v_readlane_b32 s41, v253, 56
	s_andn2_b64 vcc, exec, s[40:41]
	s_cbranch_vccnz .LBB0_257
	v_readlane_b32 s40, v253, 49
	v_readlane_b32 s41, v253, 50
	s_waitcnt lgkmcnt(0)
	v_sub_f32_e32 v115, v107, v109
	v_mul_f32_e32 v113, 0x3fb8aa3b, v109
	v_mul_f32_e32 v115, 0x3fb8aa3b, v115
	v_exp_f32_e32 v113, v113
	v_exp_f32_e32 v115, v115
	ds_write2st64_b32 v130, v109, v111 offset1:1
	ds_write2st64_b32 v130, v113, v115 offset0:2 offset1:3

; #define MFMA16(a, b, c) __builtin_amdgcn_mfma_f32_16x16x32_bf16((a), (b), (c), 0, 0, 0)
; __device__ __forceinline__ void phase_prep(const Args& a, PG8_LAS unsigned char* lds) {
;     ...
; #pragma unroll
;             for (int tj = 0; tj < 4; ++tj) {
;                 f32x4 ckk = {0.f, 0.f, 0.f, 0.f}, cqk = {0.f, 0.f, 0.f, 0.f};
; #pragma unroll
;                 for (int s = 0; s < 4; ++s) { const bf16x8 bk = (tj < 2) ? bkf[tj & 1][s] : *(const bf16x8*)(kbase + (size_t)(16 * tj + r) * 512 + 32 * s + 8 * q); ckk = MFMA16(ak[s], bk, ckk); cqk = MFMA16(aq[s], bk, cqk); }
.LBB0_259:
	s_or_b64 exec, exec, s[26:27]
	s_waitcnt vmcnt(0)
	v_mfma_f32_16x16x32_bf16 v[230:233], v[56:59], v[92:95], 0
	s_waitcnt lgkmcnt(0)
	s_barrier
	v_mfma_f32_16x16x32_bf16 v[92:95], v[60:63], v[92:95], 0
	v_readlane_b32 s40, v252, 5
	v_readlane_b32 s41, v252, 6
	v_mfma_f32_16x16x32_bf16 v[230:233], v[48:51], v[88:91], v[230:233]
	v_mfma_f32_16x16x32_bf16 v[88:91], v[52:55], v[88:91], v[92:95]
	v_mfma_f32_16x16x32_bf16 v[92:95], v[40:43], v[84:87], v[230:233]
	v_mfma_f32_16x16x32_bf16 v[230:233], v[44:47], v[84:87], v[88:91]
	s_nop 5
	ds_read_b32 v90, v137
	ds_read_b32 v89, v138 offset:256
	v_mov_b32_e32 v88, 0
	v_mov_b32_e32 v91, 0
	v_mfma_f32_16x16x32_bf16 v[84:87], v[32:35], v[80:83], v[92:95]
	v_mfma_f32_16x16x32_bf16 v[80:83], v[36:39], v[80:83], v[230:233]
	s_and_saveexec_b64 s[26:27], s[40:41]
	s_cbranch_execz .LBB0_261
	ds_read_b32 v91, v138
	s_waitcnt lgkmcnt(0)
	v_sub_f32_e32 v91, v91, v90
	v_mul_f32_e32 v91, 0x3fb8aa3b, v91
	v_exp_f32_e32 v91, v91
